# P0 W1gu transpose tiles spread over all 256 workgroups (wave-major item index)
# baseline (speedup 1.0000x reference)
; #define LAS __attribute__((address_space(3)))
; #define OPAQUE_TID() int tid = threadIdx.x; asm volatile("" : "+v"(tid)); const int lane = tid & 63; const int wave = __builtin_amdgcn_readfirstlane(tid >> 6); (void)lane; (void)wave
; __global__ void __launch_bounds__(NWAVES * 64, 2) mega_fwd(Args args) {
;     ...
;     if (IN(0)) {
;         OPAQUE_TID();
;         const int gw = vcu * NWAVES + wave, NGW = G * NWAVES;
;         LAS float* scr = (LAS float*)(lds + wave * 16384);
;         constexpr int I_GU = (DM / 64) * (FF / 64), I_D = (FF / 64) * (DM / 64), I_IN = (DM / 64) * (NIN / 64), I_GLU = (512 / 64) * (512 / 64), I_BR = (512 / 64) * (DM / 64), I_SQ = (DM / 64) * (DM / 64), I_PP = (PLE / 64) * (DM / 64);
;         for (int it = gw; it < 2 * I_GU; it += NGW) {
;             if (it < I_GU) p0_transpose_item(args.in[3], DM, FF, W1gu, args.in[2], 1, scr, it, lane);
;             else p0_transpose_item(args.in[4], DM, FF, W1gu, args.in[2], 2, scr, it - I_GU, lane);
;         }
.LBB0_24:
	s_add_u32 s90, s66, 0x10000
	s_addc_u32 s91, s67, 0
	s_add_u32 s0, s66, 0x20000
	s_addc_u32 s1, s67, 0
	s_add_u32 s92, s66, 0x30000
	v_writelane_b32 v251, s14, 18
	s_addc_u32 s93, s67, 0
	s_add_u32 s4, s66, 0xf00000
	v_writelane_b32 v251, s15, 19
	v_writelane_b32 v251, s0, 20
	s_addc_u32 s5, s67, 0
	s_nop 0
	v_writelane_b32 v251, s1, 21
	s_add_u32 s0, s66, 0x4500000
	s_addc_u32 s1, s67, 0
	v_writelane_b32 v251, s0, 22
	s_cmp_lt_i32 s84, 1
	s_nop 0
	v_writelane_b32 v251, s1, 23
	s_cselect_b64 s[0:1], -1, 0
	s_cmp_gt_i32 s85, 0
	s_cselect_b64 s[2:3], -1, 0
	s_and_b64 s[6:7], s[0:1], s[2:3]
	s_andn2_b64 vcc, exec, s[6:7]
	s_cbranch_vccnz .LBB0_92
	v_mov_b32_e32 v1, v0
	s_nop 0
	v_readfirstlane_b32 s0, v1
	s_ashr_i32 s16, s0, 6
	v_readlane_b32 s0, v251, 17
	s_lshl_b32 s1, s16, 8
	v_and_b32_e32 v79, 63, v1
	s_add_i32 s17, s0, s1
	s_lshl_b32 s0, s86, 3
	s_cmpk_gt_i32 s17, 0x57f
	v_lshlrev_b32_e32 v66, 4, v79
	v_lshlrev_b32_e32 v68, 3, v79
	s_cbranch_scc1 .LBB0_64
	s_lshl_b32 s2, s16, 14
	s_add_i32 s8, s2, 0
	v_mov_b32_e32 v71, 0
	v_and_b32_e32 v2, 56, v68
	v_lshrrev_b32_e32 v67, 3, v79
	s_cmp_lg_u64 s[72:73], 0
	v_mul_u32_u24_e32 v4, 0x84, v2
	v_lshlrev_b32_e32 v2, 1, v2
	v_mov_b32_e32 v3, v71
	s_cselect_b64 s[2:3], -1, 0
	v_lshl_add_u64 v[74:75], s[4:5], 0, v[2:3]
	v_lshlrev_b32_e32 v2, 2, v67
	v_and_b32_e32 v70, 0x70, v66
	v_add3_u32 v89, s8, v4, v2
	v_cndmask_b32_e64 v2, 0, 1, s[2:3]
	s_mov_b32 s9, 0
	v_lshl_add_u64 v[72:73], s[76:77], 0, v[70:71]
	v_add_u32_e32 v69, s8, v70
	v_mul_u32_u24_e32 v81, 0x84, v67
	v_or_b32_e32 v83, 8, v67
	v_or_b32_e32 v85, 16, v67
	v_or_b32_e32 v87, 24, v67
	v_lshl_add_u64 v[76:77], s[74:75], 0, v[70:71]
	s_lshl_b32 s14, s17, 6
	s_lshl_b32 s15, s86, 9
	s_lshl_b32 s18, s17, 7
	s_lshl_b32 s19, s86, 10
	v_cmp_ne_u32_e64 s[2:3], 1, v2
	s_movk_i32 s20, 0x7fff
	s_mov_b32 s21, 0xffff0000
	s_movk_i32 s22, 0x2c00
	s_mov_b32 s23, s17
	s_branch .LBB0_29
